# GEMM per-tile accumulator zeroing with v_mov_b64 (64 instead of 127 moves per tile per wave)
# speedup vs baseline: 1.0027x; 1.0027x over previous
;     __host__ __device__ bool next(int i, Unit& u) const { const int L = i * G + c; if (L >= 32) return false; u.pm = L; u.pn = L >> 4; return true; }
; template <class Epi, class Sched>
; __device__ __forceinline__ void gemm_phase(LAS unsigned char* lds, const Gemm g, const Sched S, const Epi E, const int tid) {
;     ...
;         const bool has_next = S.next(ui + 1, nxt);
;         const char* nA = has_next ? (const char*)g.A + (size_t)nxt.pm * tstepA : cA; const char* nB = has_next ? (const char*)g.Bt + (size_t)nxt.pn * tstepB : cB;
;     ...
; #pragma unroll
;         for (int a = 0; a < 2; ++a)
; #pragma unroll
;             for (int b = 0; b < 2; ++b)
; #pragma unroll
;                 for (int m = 0; m < 4; ++m)
; #pragma unroll
;                     for (int n = 0; n < 2; ++n) acc[a][b][m][n] = (f32x4){0.f, 0.f, 0.f, 0.f};
;         cur = nxt; cA = nA; cB = nB; ++ui;
.LBB0_298:
	s_add_i32 s88, s88, 1
	s_mov_b64 s[26:27], s[4:5]
	s_mul_i32 s4, s88, s58
	s_mov_b32 s10, s89
	s_mov_b32 s92, s89
	s_add_i32 s89, s4, s36
	s_cmp_lt_i32 s89, 32
	s_mov_b32 s11, s90
	s_mov_b32 s91, s90
	s_cselect_b64 s[20:21], -1, 0
	s_ashr_i32 s90, s89, 4
	s_and_b64 s[4:5], s[20:21], exec
	s_mov_b64 s[22:23], s[14:15]
	s_cselect_b32 s14, s89, s10
	s_cselect_b32 s4, s90, s11
	s_ashr_i32 s15, s14, 31
	s_lshl_b64 s[14:15], s[14:15], 19
	s_add_u32 s14, s40, s14
	s_addc_u32 s15, s41, s15
	s_and_b64 s[28:29], s[20:21], exec
	s_cselect_b32 s93, s15, s23
	s_cselect_b32 s94, s14, s22
	s_ashr_i32 s5, s4, 31
	s_lshl_b64 s[4:5], s[4:5], 20
	s_add_u32 s4, s42, s4
	s_addc_u32 s5, s43, s5
	s_and_b64 s[28:29], s[20:21], exec
	s_cselect_b32 s95, s5, s27
	s_cselect_b32 s96, s4, s26
	s_add_u32 s97, s26, 0x100
	s_addc_u32 vcc_lo, s27, 0
	s_add_u32 s22, s22, 0x40080
	v_mov_b32_e32 v2, 0
	s_addc_u32 s23, s23, 0
	s_mov_b32 vcc_hi, -2
	v_mov_b32_e32 v3, v2
	v_mov_b64_e32 v[4:5], v[2:3]
	v_mov_b64_e32 v[6:7], v[2:3]
	v_mov_b64_e32 v[8:9], v[2:3]
	v_mov_b64_e32 v[10:11], v[2:3]
	v_mov_b64_e32 v[12:13], v[2:3]
	v_mov_b64_e32 v[14:15], v[2:3]
	v_mov_b64_e32 v[16:17], v[2:3]
	v_mov_b64_e32 v[18:19], v[2:3]
	v_mov_b64_e32 v[20:21], v[2:3]
	v_mov_b64_e32 v[22:23], v[2:3]
	v_mov_b64_e32 v[24:25], v[2:3]
	v_mov_b64_e32 v[26:27], v[2:3]
	v_mov_b64_e32 v[28:29], v[2:3]
	v_mov_b64_e32 v[30:31], v[2:3]
	v_mov_b64_e32 v[32:33], v[2:3]
	v_mov_b64_e32 v[34:35], v[2:3]
	v_mov_b64_e32 v[36:37], v[2:3]
	v_mov_b64_e32 v[38:39], v[2:3]
	v_mov_b64_e32 v[40:41], v[2:3]
	v_mov_b64_e32 v[42:43], v[2:3]
	v_mov_b64_e32 v[44:45], v[2:3]
	v_mov_b64_e32 v[46:47], v[2:3]
	v_mov_b64_e32 v[48:49], v[2:3]
	v_mov_b64_e32 v[50:51], v[2:3]
	v_mov_b64_e32 v[52:53], v[2:3]
	v_mov_b64_e32 v[54:55], v[2:3]
	v_mov_b64_e32 v[56:57], v[2:3]
	v_mov_b64_e32 v[58:59], v[2:3]
	v_mov_b64_e32 v[60:61], v[2:3]
	v_mov_b64_e32 v[62:63], v[2:3]
	v_mov_b64_e32 v[64:65], v[2:3]
	v_mov_b64_e32 v[66:67], v[2:3]
	v_mov_b64_e32 v[68:69], v[2:3]
	v_mov_b64_e32 v[70:71], v[2:3]
	v_mov_b64_e32 v[72:73], v[2:3]
	v_mov_b64_e32 v[74:75], v[2:3]
	v_mov_b64_e32 v[76:77], v[2:3]
	v_mov_b64_e32 v[78:79], v[2:3]
	v_mov_b64_e32 v[80:81], v[2:3]
	v_mov_b64_e32 v[82:83], v[2:3]
	v_mov_b64_e32 v[84:85], v[2:3]
	v_mov_b64_e32 v[86:87], v[2:3]
	v_mov_b64_e32 v[88:89], v[2:3]
	v_mov_b64_e32 v[90:91], v[2:3]
	v_mov_b64_e32 v[92:93], v[2:3]
	v_mov_b64_e32 v[94:95], v[2:3]
	v_mov_b64_e32 v[96:97], v[2:3]
	v_mov_b64_e32 v[106:107], v[2:3]
	v_mov_b64_e32 v[108:109], v[2:3]
	v_mov_b64_e32 v[110:111], v[2:3]
	v_mov_b64_e32 v[112:113], v[2:3]
	v_mov_b64_e32 v[114:115], v[2:3]
	v_mov_b64_e32 v[116:117], v[2:3]
	v_mov_b64_e32 v[118:119], v[2:3]
	v_mov_b64_e32 v[120:121], v[2:3]
	v_mov_b64_e32 v[122:123], v[2:3]
	v_mov_b64_e32 v[124:125], v[2:3]
	v_mov_b64_e32 v[126:127], v[2:3]
	v_mov_b64_e32 v[128:129], v[2:3]
	v_mov_b64_e32 v[130:131], v[2:3]
	v_mov_b64_e32 v[132:133], v[2:3]
	v_mov_b64_e32 v[134:135], v[2:3]
	v_mov_b64_e32 v[136:137], v[2:3]
	s_waitcnt vmcnt(0)

;     __host__ __device__ bool next(int i, Unit& u) const { const int L = i * G + c; if (L >= 32) return false; u.pm = L; u.pn = L >> 4; return true; }
; template <class Epi, class Sched>
; __device__ __forceinline__ void gemm_phase(LAS unsigned char* lds, const Gemm g, const Sched S, const Epi E, const int tid) {
;     ...
;         const bool has_next = S.next(ui + 1, nxt);
;         const char* nA = has_next ? (const char*)g.A + (size_t)nxt.pm * tstepA : cA; const char* nB = has_next ? (const char*)g.Bt + (size_t)nxt.pn * tstepB : cB;
;     ...
; #pragma unroll
;         for (int a = 0; a < 2; ++a)
; #pragma unroll
;             for (int b = 0; b < 2; ++b)
; #pragma unroll
;                 for (int m = 0; m < 4; ++m)
; #pragma unroll
;                     for (int n = 0; n < 2; ++n) acc[a][b][m][n] = (f32x4){0.f, 0.f, 0.f, 0.f};
;         cur = nxt; cA = nA; cB = nB; ++ui;
.LBB0_331:
	s_xor_b64 s[8:9], s[8:9], -1
	s_and_b64 s[42:43], s[28:29], s[42:43]
	s_mov_b64 s[10:11], s[4:5]
	s_and_b64 s[4:5], s[42:43], exec
	s_cselect_b32 s4, s25, s25
	s_ashr_i32 s5, s4, 31
	s_lshl_b64 s[4:5], s[4:5], 19
	s_add_u32 s4, s34, s4
	s_addc_u32 s5, s35, s5
	s_and_b64 s[46:47], s[42:43], exec
	s_cselect_b32 s7, s5, s11
	s_cselect_b32 s92, s4, s10
	s_cselect_b32 s93, s41, s45
	s_cselect_b32 s94, s40, s44
	s_add_u32 s95, s44, 0x100
	s_addc_u32 s96, s45, 0
	s_add_u32 s44, s10, 0x40080
	v_mov_b32_e32 v2, 0
	s_addc_u32 s45, s11, 0
	s_mov_b32 s97, -2
	v_mov_b32_e32 v3, v2
	v_mov_b64_e32 v[4:5], v[2:3]
	v_mov_b64_e32 v[6:7], v[2:3]
	v_mov_b64_e32 v[8:9], v[2:3]
	v_mov_b64_e32 v[10:11], v[2:3]
	v_mov_b64_e32 v[12:13], v[2:3]
	v_mov_b64_e32 v[14:15], v[2:3]
	v_mov_b64_e32 v[16:17], v[2:3]
	v_mov_b64_e32 v[18:19], v[2:3]
	v_mov_b64_e32 v[20:21], v[2:3]
	v_mov_b64_e32 v[22:23], v[2:3]
	v_mov_b64_e32 v[24:25], v[2:3]
	v_mov_b64_e32 v[26:27], v[2:3]
	v_mov_b64_e32 v[28:29], v[2:3]
	v_mov_b64_e32 v[30:31], v[2:3]
	v_mov_b64_e32 v[32:33], v[2:3]
	v_mov_b64_e32 v[34:35], v[2:3]
	v_mov_b64_e32 v[36:37], v[2:3]
	v_mov_b64_e32 v[38:39], v[2:3]
	v_mov_b64_e32 v[40:41], v[2:3]
	v_mov_b64_e32 v[42:43], v[2:3]
	v_mov_b64_e32 v[44:45], v[2:3]
	v_mov_b64_e32 v[46:47], v[2:3]
	v_mov_b64_e32 v[48:49], v[2:3]
	v_mov_b64_e32 v[50:51], v[2:3]
	v_mov_b64_e32 v[52:53], v[2:3]
	v_mov_b64_e32 v[54:55], v[2:3]
	v_mov_b64_e32 v[56:57], v[2:3]
	v_mov_b64_e32 v[58:59], v[2:3]
	v_mov_b64_e32 v[60:61], v[2:3]
	v_mov_b64_e32 v[62:63], v[2:3]
	v_mov_b64_e32 v[64:65], v[2:3]
	v_mov_b64_e32 v[66:67], v[2:3]
	v_mov_b64_e32 v[68:69], v[2:3]
	v_mov_b64_e32 v[70:71], v[2:3]
	v_mov_b64_e32 v[72:73], v[2:3]
	v_mov_b64_e32 v[74:75], v[2:3]
	v_mov_b64_e32 v[76:77], v[2:3]
	v_mov_b64_e32 v[78:79], v[2:3]
	v_mov_b64_e32 v[80:81], v[2:3]
	v_mov_b64_e32 v[82:83], v[2:3]
	v_mov_b64_e32 v[84:85], v[2:3]
	v_mov_b64_e32 v[86:87], v[2:3]
	v_mov_b64_e32 v[88:89], v[2:3]
	v_mov_b64_e32 v[90:91], v[2:3]
	v_mov_b64_e32 v[92:93], v[2:3]
	v_mov_b64_e32 v[94:95], v[2:3]
	v_mov_b64_e32 v[96:97], v[2:3]
	v_mov_b64_e32 v[98:99], v[2:3]
	v_mov_b64_e32 v[100:101], v[2:3]
	v_mov_b64_e32 v[102:103], v[2:3]
	v_mov_b64_e32 v[104:105], v[2:3]
	v_mov_b64_e32 v[106:107], v[2:3]
	v_mov_b64_e32 v[108:109], v[2:3]
	v_mov_b64_e32 v[110:111], v[2:3]
	v_mov_b64_e32 v[112:113], v[2:3]
	v_mov_b64_e32 v[114:115], v[2:3]
	v_mov_b64_e32 v[116:117], v[2:3]
	v_mov_b64_e32 v[118:119], v[2:3]
	v_mov_b64_e32 v[120:121], v[2:3]
	v_mov_b64_e32 v[122:123], v[2:3]
	v_mov_b64_e32 v[124:125], v[2:3]
	v_mov_b64_e32 v[126:127], v[2:3]
	v_mov_b64_e32 v[128:129], v[2:3]

;     __host__ __device__ bool next(int i, Unit& u) const { const int L = i * G + c; if (L >= 32) return false; u.pm = L; u.pn = L >> 4; return true; }
; template <class Epi, class Sched>
; __device__ __forceinline__ void gemm_phase(LAS unsigned char* lds, const Gemm g, const Sched S, const Epi E, const int tid) {
;     ...
;         const bool has_next = S.next(ui + 1, nxt);
;         const char* nA = has_next ? (const char*)g.A + (size_t)nxt.pm * tstepA : cA; const char* nB = has_next ? (const char*)g.Bt + (size_t)nxt.pn * tstepB : cB;
;     ...
; #pragma unroll
;         for (int a = 0; a < 2; ++a)
; #pragma unroll
;             for (int b = 0; b < 2; ++b)
; #pragma unroll
;                 for (int m = 0; m < 4; ++m)
; #pragma unroll
;                     for (int n = 0; n < 2; ++n) acc[a][b][m][n] = (f32x4){0.f, 0.f, 0.f, 0.f};
;         cur = nxt; cA = nA; cB = nB; ++ui;
.LBB0_470:
	s_ashr_i32 s45, s44, 31
	s_lshl_b64 s[4:5], s[44:45], 19
	s_add_u32 s46, s34, s4
	s_addc_u32 s47, s35, s5
	s_and_b64 s[4:5], s[6:7], exec
	s_cselect_b32 s9, s47, s13
	s_cselect_b32 s45, s46, s12
	s_ashr_i32 s43, s42, 31
	s_lshl_b64 s[4:5], s[42:43], 19
	s_add_u32 s4, s88, s4
	s_addc_u32 s5, s89, s5
	s_and_b64 s[14:15], s[6:7], exec
	s_cselect_b32 s43, s5, s11
	s_cselect_b32 s48, s4, s10
	s_add_u32 s49, s10, 0x100
	s_addc_u32 s62, s11, 0
	s_add_u32 s10, s12, 0x40080
	v_mov_b32_e32 v2, 0
	s_addc_u32 s11, s13, 0
	s_mov_b32 s82, -2
	v_mov_b32_e32 v3, v2
	v_mov_b64_e32 v[4:5], v[2:3]
	v_mov_b64_e32 v[6:7], v[2:3]
	v_mov_b64_e32 v[8:9], v[2:3]
	v_mov_b64_e32 v[10:11], v[2:3]
	v_mov_b64_e32 v[12:13], v[2:3]
	v_mov_b64_e32 v[14:15], v[2:3]
	v_mov_b64_e32 v[16:17], v[2:3]
	v_mov_b64_e32 v[18:19], v[2:3]
	v_mov_b64_e32 v[20:21], v[2:3]
	v_mov_b64_e32 v[22:23], v[2:3]
	v_mov_b64_e32 v[24:25], v[2:3]
	v_mov_b64_e32 v[26:27], v[2:3]
	v_mov_b64_e32 v[28:29], v[2:3]
	v_mov_b64_e32 v[30:31], v[2:3]
	v_mov_b64_e32 v[32:33], v[2:3]
	v_mov_b64_e32 v[34:35], v[2:3]
	v_mov_b64_e32 v[36:37], v[2:3]
	v_mov_b64_e32 v[38:39], v[2:3]
	v_mov_b64_e32 v[40:41], v[2:3]
	v_mov_b64_e32 v[42:43], v[2:3]
	v_mov_b64_e32 v[44:45], v[2:3]
	v_mov_b64_e32 v[46:47], v[2:3]
	v_mov_b64_e32 v[48:49], v[2:3]
	v_mov_b64_e32 v[54:55], v[2:3]
	v_mov_b64_e32 v[56:57], v[2:3]
	v_mov_b64_e32 v[58:59], v[2:3]
	v_mov_b64_e32 v[60:61], v[2:3]
	v_mov_b64_e32 v[62:63], v[2:3]
	v_mov_b64_e32 v[64:65], v[2:3]
	v_mov_b64_e32 v[66:67], v[2:3]
	v_mov_b64_e32 v[68:69], v[2:3]
	v_mov_b64_e32 v[70:71], v[2:3]
	v_mov_b64_e32 v[72:73], v[2:3]
	v_mov_b64_e32 v[74:75], v[2:3]
	v_mov_b64_e32 v[76:77], v[2:3]
	v_mov_b64_e32 v[78:79], v[2:3]
	v_mov_b64_e32 v[80:81], v[2:3]
	v_mov_b64_e32 v[82:83], v[2:3]
	v_mov_b64_e32 v[84:85], v[2:3]
	v_mov_b64_e32 v[86:87], v[2:3]
	v_mov_b64_e32 v[88:89], v[2:3]
	v_mov_b64_e32 v[90:91], v[2:3]
	v_mov_b64_e32 v[92:93], v[2:3]
	v_mov_b64_e32 v[94:95], v[2:3]
	v_mov_b64_e32 v[96:97], v[2:3]
	v_mov_b64_e32 v[98:99], v[2:3]
	v_mov_b64_e32 v[100:101], v[2:3]
	v_mov_b64_e32 v[106:107], v[2:3]
	v_mov_b64_e32 v[108:109], v[2:3]
	v_mov_b64_e32 v[110:111], v[2:3]
	v_mov_b64_e32 v[112:113], v[2:3]
	v_mov_b64_e32 v[114:115], v[2:3]
	v_mov_b64_e32 v[116:117], v[2:3]
	v_mov_b64_e32 v[118:119], v[2:3]
	v_mov_b64_e32 v[120:121], v[2:3]
	v_mov_b64_e32 v[122:123], v[2:3]
	v_mov_b64_e32 v[124:125], v[2:3]
	v_mov_b64_e32 v[126:127], v[2:3]
	v_mov_b64_e32 v[128:129], v[2:3]
	v_mov_b64_e32 v[130:131], v[2:3]
	v_mov_b64_e32 v[132:133], v[2:3]
	v_mov_b64_e32 v[134:135], v[2:3]
	v_mov_b64_e32 v[136:137], v[2:3]
	s_waitcnt vmcnt(0)

; template <class Epi, class Sched>
; __device__ __forceinline__ void gemm_phase(LAS unsigned char* lds, const Gemm g, const Sched S, const Epi E, const int tid) {
;     ...
; #pragma unroll
;         for (int a = 0; a < 2; ++a)
; #pragma unroll
;             for (int b = 0; b < 2; ++b)
; #pragma unroll
;                 for (int m = 0; m < 4; ++m)
; #pragma unroll
;                     for (int n = 0; n < 2; ++n) acc[a][b][m][n] = (f32x4){0.f, 0.f, 0.f, 0.f};
;         cur = nxt; cA = nA; cB = nB; ++ui;
.LBB0_777:
	s_add_u32 s92, s18, 0x100
	s_addc_u32 s93, s19, 0
	s_add_u32 s18, s20, 0x80
	v_mov_b32_e32 v2, 0
	s_addc_u32 s19, s21, 0
	s_mov_b32 s20, 0
	s_waitcnt lgkmcnt(0)
	v_mov_b32_e32 v3, v2
	v_mov_b64_e32 v[4:5], v[2:3]
	v_mov_b64_e32 v[6:7], v[2:3]
	v_mov_b64_e32 v[8:9], v[2:3]
	v_mov_b64_e32 v[10:11], v[2:3]
	v_mov_b64_e32 v[12:13], v[2:3]
	v_mov_b64_e32 v[14:15], v[2:3]
	v_mov_b64_e32 v[16:17], v[2:3]
	v_mov_b64_e32 v[18:19], v[2:3]
	v_mov_b64_e32 v[20:21], v[2:3]
	v_mov_b64_e32 v[22:23], v[2:3]
	v_mov_b64_e32 v[24:25], v[2:3]
	v_mov_b64_e32 v[26:27], v[2:3]
	v_mov_b64_e32 v[28:29], v[2:3]
	v_mov_b64_e32 v[30:31], v[2:3]
	v_mov_b64_e32 v[32:33], v[2:3]
	v_mov_b64_e32 v[34:35], v[2:3]
	v_mov_b64_e32 v[36:37], v[2:3]
	v_mov_b64_e32 v[38:39], v[2:3]
	v_mov_b64_e32 v[40:41], v[2:3]
	v_mov_b64_e32 v[42:43], v[2:3]
	v_mov_b64_e32 v[44:45], v[2:3]
	v_mov_b64_e32 v[46:47], v[2:3]
	v_mov_b64_e32 v[48:49], v[2:3]
	v_mov_b64_e32 v[50:51], v[2:3]
	v_mov_b64_e32 v[52:53], v[2:3]
	v_mov_b64_e32 v[54:55], v[2:3]
	v_mov_b64_e32 v[56:57], v[2:3]
	v_mov_b64_e32 v[58:59], v[2:3]
	v_mov_b64_e32 v[60:61], v[2:3]
	v_mov_b64_e32 v[62:63], v[2:3]
	v_mov_b64_e32 v[64:65], v[2:3]
	v_mov_b64_e32 v[66:67], v[2:3]
	v_mov_b64_e32 v[68:69], v[2:3]
	v_mov_b64_e32 v[70:71], v[2:3]
	v_mov_b64_e32 v[72:73], v[2:3]
	v_mov_b64_e32 v[74:75], v[2:3]
	v_mov_b64_e32 v[76:77], v[2:3]
	v_mov_b64_e32 v[78:79], v[2:3]
	v_mov_b64_e32 v[80:81], v[2:3]
	v_mov_b64_e32 v[82:83], v[2:3]
	v_mov_b64_e32 v[84:85], v[2:3]
	v_mov_b64_e32 v[86:87], v[2:3]
	v_mov_b64_e32 v[88:89], v[2:3]
	v_mov_b64_e32 v[90:91], v[2:3]
	v_mov_b64_e32 v[92:93], v[2:3]
	v_mov_b64_e32 v[94:95], v[2:3]
	v_mov_b64_e32 v[96:97], v[2:3]
	v_mov_b64_e32 v[98:99], v[2:3]
	v_mov_b64_e32 v[100:101], v[2:3]
	v_mov_b64_e32 v[102:103], v[2:3]
	v_mov_b64_e32 v[104:105], v[2:3]
	v_mov_b64_e32 v[106:107], v[2:3]
	v_mov_b64_e32 v[108:109], v[2:3]
	v_mov_b64_e32 v[110:111], v[2:3]
	v_mov_b64_e32 v[112:113], v[2:3]
	v_mov_b64_e32 v[114:115], v[2:3]
	v_mov_b64_e32 v[116:117], v[2:3]
	v_mov_b64_e32 v[118:119], v[2:3]
	v_mov_b64_e32 v[120:121], v[2:3]
	v_mov_b64_e32 v[122:123], v[2:3]
	v_mov_b64_e32 v[124:125], v[2:3]
	v_mov_b64_e32 v[130:131], v[2:3]
	v_mov_b64_e32 v[132:133], v[2:3]
	s_waitcnt vmcnt(0)

;     __host__ __device__ bool next(int i, Unit& u) const { const int L = i * G + c; if (L >= 32) return false; u.pm = L; u.pn = L >> 4; return true; }
; template <class Epi, class Sched>
; __device__ __forceinline__ void gemm_phase(LAS unsigned char* lds, const Gemm g, const Sched S, const Epi E, const int tid) {
;     ...
;         const bool has_next = S.next(ui + 1, nxt);
;         const char* nA = has_next ? (const char*)g.A + (size_t)nxt.pm * tstepA : cA; const char* nB = has_next ? (const char*)g.Bt + (size_t)nxt.pn * tstepB : cB;
;     ...
; #pragma unroll
;         for (int a = 0; a < 2; ++a)
; #pragma unroll
;             for (int b = 0; b < 2; ++b)
; #pragma unroll
;                 for (int m = 0; m < 4; ++m)
; #pragma unroll
;                     for (int n = 0; n < 2; ++n) acc[a][b][m][n] = (f32x4){0.f, 0.f, 0.f, 0.f};
;         cur = nxt; cA = nA; cB = nB; ++ui;
.LBB0_818:
	s_ashr_i32 s17, s16, 31
	s_lshl_b64 s[18:19], s[16:17], 19
	s_add_u32 s18, s34, s18
	s_addc_u32 s19, s35, s19
	s_and_b64 s[20:21], s[6:7], exec
	s_cselect_b32 s9, s19, s25
	s_cselect_b32 s17, s18, s24
	s_ashr_i32 s15, s14, 31
	s_lshl_b64 s[20:21], s[14:15], 19
	s_add_u32 s20, s29, s20
	s_addc_u32 s21, s31, s21
	s_and_b64 s[26:27], s[6:7], exec
	s_cselect_b32 s15, s21, s23
	s_cselect_b32 s69, s20, s22
	s_add_u32 s82, s22, 0x100
	s_addc_u32 s83, s23, 0
	s_add_u32 s22, s24, 0x40080
	v_mov_b32_e32 v2, 0
	s_addc_u32 s23, s25, 0
	s_mov_b32 s84, -2
	v_mov_b32_e32 v3, v2
	v_mov_b64_e32 v[4:5], v[2:3]
	v_mov_b64_e32 v[6:7], v[2:3]
	v_mov_b64_e32 v[8:9], v[2:3]
	v_mov_b64_e32 v[10:11], v[2:3]
	v_mov_b64_e32 v[12:13], v[2:3]
	v_mov_b64_e32 v[14:15], v[2:3]
	v_mov_b64_e32 v[16:17], v[2:3]
	v_mov_b64_e32 v[18:19], v[2:3]
	v_mov_b64_e32 v[20:21], v[2:3]
	v_mov_b64_e32 v[22:23], v[2:3]
	v_mov_b64_e32 v[24:25], v[2:3]
	v_mov_b64_e32 v[26:27], v[2:3]
	v_mov_b64_e32 v[28:29], v[2:3]
	v_mov_b64_e32 v[30:31], v[2:3]
	v_mov_b64_e32 v[32:33], v[2:3]
	v_mov_b64_e32 v[34:35], v[2:3]
	v_mov_b64_e32 v[36:37], v[2:3]
	v_mov_b64_e32 v[38:39], v[2:3]
	v_mov_b64_e32 v[40:41], v[2:3]
	v_mov_b64_e32 v[42:43], v[2:3]
	v_mov_b64_e32 v[44:45], v[2:3]
	v_mov_b64_e32 v[46:47], v[2:3]
	v_mov_b64_e32 v[48:49], v[2:3]
	v_mov_b64_e32 v[50:51], v[2:3]
	v_mov_b64_e32 v[52:53], v[2:3]
	v_mov_b64_e32 v[54:55], v[2:3]
	v_mov_b64_e32 v[56:57], v[2:3]
	v_mov_b64_e32 v[58:59], v[2:3]
	v_mov_b64_e32 v[60:61], v[2:3]
	v_mov_b64_e32 v[62:63], v[2:3]
	v_mov_b64_e32 v[64:65], v[2:3]
	v_mov_b64_e32 v[66:67], v[2:3]
	v_mov_b64_e32 v[68:69], v[2:3]
	v_mov_b64_e32 v[70:71], v[2:3]
	v_mov_b64_e32 v[72:73], v[2:3]
	v_mov_b64_e32 v[74:75], v[2:3]
	v_mov_b64_e32 v[76:77], v[2:3]
	v_mov_b64_e32 v[78:79], v[2:3]
	v_mov_b64_e32 v[80:81], v[2:3]
	v_mov_b64_e32 v[82:83], v[2:3]
	v_mov_b64_e32 v[84:85], v[2:3]
	v_mov_b64_e32 v[86:87], v[2:3]
	v_mov_b64_e32 v[88:89], v[2:3]
	v_mov_b64_e32 v[90:91], v[2:3]
	v_mov_b64_e32 v[92:93], v[2:3]
	v_mov_b64_e32 v[94:95], v[2:3]
	v_mov_b64_e32 v[96:97], v[2:3]
	v_mov_b64_e32 v[102:103], v[2:3]
	v_mov_b64_e32 v[104:105], v[2:3]
	v_mov_b64_e32 v[106:107], v[2:3]
	v_mov_b64_e32 v[108:109], v[2:3]
	v_mov_b64_e32 v[110:111], v[2:3]
	v_mov_b64_e32 v[112:113], v[2:3]
	v_mov_b64_e32 v[114:115], v[2:3]
	v_mov_b64_e32 v[116:117], v[2:3]
	v_mov_b64_e32 v[118:119], v[2:3]
	v_mov_b64_e32 v[120:121], v[2:3]
	v_mov_b64_e32 v[122:123], v[2:3]
	v_mov_b64_e32 v[124:125], v[2:3]
	v_mov_b64_e32 v[126:127], v[2:3]
	v_mov_b64_e32 v[128:129], v[2:3]
	v_mov_b64_e32 v[130:131], v[2:3]
	v_mov_b64_e32 v[132:133], v[2:3]
	s_waitcnt vmcnt(0)
